# v45 plus: attention items run waves 4-7 at static priority 1 (reset at item end)
# speedup vs baseline: 1.0118x; 1.0005x over previous
; DI void attn_item(const Params& p, int seq, int hd, int qblk, char* smem, int tid_) {
;   const u16* qb = (const u16*)(p.ws + OFF_Q);
;   const u16* kb = (const u16*)(p.ws + OFF_K);
;   const u16* vt = (const u16*)(p.ws + OFF_VT);
;   u16* mixed = (u16*)(p.ws + OFF_H);
;   int tid = tid_;
;   asm volatile("" : "+v"(tid));
;   const int lane = tid & 63, w = tid >> 6, r = lane & 31, h = lane >> 5;
;   const size_t qrow = (size_t)seq * 2048 + qblk * 256 + w * 32 + r;
;   bf16x8 qf[12];
; #pragma unroll
;   for (int s = 0; s < 12; s++) qf[s] = *(const bf16x8*)(qb + qrow * 768 + hd * 192 + 16 * s + 8 * h);
;   f32x16 o[4];
; #pragma unroll
;   for (int db = 0; db < 4; db++)
; #pragma unroll
;     for (int i = 0; i < 16; i++) o[db][i] = 0.f;
;   float m = -1e30f, lsum = 0.f;
;   const u16* kg = kb + ((size_t)seq * 2048 + (tid >> 3)) * 768 + hd * 192 + (tid & 7) * 8;
;   const int kl = (tid >> 3) * 200 + (tid & 7) * 8;
;   const u16* vg = vt + ((size_t)(seq * 4 + hd) * 128 + (tid >> 3)) * 2048 + (tid & 7) * 8;
;   const int vl = (tid >> 3) * 72 + (tid & 7) * 8;
;   u32x4 rk[3], rv[2];
; #pragma unroll
;   for (int i = 0; i < 3; i++) rk[i] = *(const u32x4*)(kg + 64 * i);
; #pragma unroll
;   for (int i = 0; i < 2; i++) rv[i] = *(const u32x4*)(vg + (size_t)(64 * i) * 2048);
;   __syncthreads();
;   {
;     u16* sK0 = (u16*)smem;
;     u16* sV0 = sK0 + 64 * 200;
; #pragma unroll
;     for (int i = 0; i < 3; i++) *(u32x4*)(sK0 + kl + 64 * i) = rk[i];
; #pragma unroll
;     for (int i = 0; i < 2; i++) *(u32x4*)(sV0 + vl + 64 * i * 72) = rv[i];
;   }
;   __syncthreads();
; #pragma unroll
;   for (int i = 0; i < 3; i++) rk[i] = *(const u32x4*)(kg + (size_t)64 * 768 + 64 * i);
; #pragma unroll
;   for (int i = 0; i < 2; i++) rv[i] = *(const u32x4*)(vg + (size_t)(64 * i) * 2048 + 64);
; DI void run_phase(const Params& p, int ph, char* smem, int* s_item, const XcdBarrier* xbp) {
;     ...
;           const int a = it - 144;
;           attn_item(p, a >> 5, (a >> 3) & 3, a & 7, smem, tid);
.LBB0_620:
	s_or_b64 exec, exec, s[2:3]
	v_mov_b32_e32 v0, s45
	s_waitcnt lgkmcnt(0)
	s_barrier
	ds_read_b32 v0, v0
	s_mov_b64 s[2:3], -1
	s_waitcnt lgkmcnt(0)
	v_readfirstlane_b32 s42, v0
	s_cmpk_gt_i32 s42, 0x68f
	s_cbranch_scc1 .LBB0_615
	v_readfirstlane_b32 s23, v233
	s_ashr_i32 s26, s23, 6
	s_ashr_i32 s97, s23, 8
	s_cmp_gt_i32 s42, 47
	s_cbranch_scc0 .LBB0_647
	s_cmpk_gt_u32 s42, 0x8f
	s_cbranch_scc0 .LBB0_635
	s_cmpk_lt_u32 s23, 0x100
	s_cbranch_scc1 .Lprio_skip
	s_setprio 1
.Lprio_skip:
	s_add_i32 s1, s42, 0xffffff70
	s_lshr_b32 s5, s1, 5
	v_mov_b32_e32 v36, v233
	s_lshl_b32 s3, s42, 8
	s_lshl_b32 s2, s5, 11
	s_and_b32 s3, s3, 0x700
	v_ashrrev_i32_e32 v20, 3, v36
	s_or_b32 s88, s2, s3
	v_ashrrev_i32_e32 v0, 1, v36
	s_mov_b32 s3, s89
	v_ashrrev_i32_e32 v21, 31, v20
	v_and_b32_e32 v0, 0xffffffe0, v0
	v_lshl_add_u64 v[22:23], v[20:21], 0, s[2:3]
	v_readlane_b32 s2, v246, 25
	v_ashrrev_i32_e32 v1, 31, v0
	v_readlane_b32 s3, v246, 26
	s_movk_i32 s8, 0x600
	v_lshl_add_u64 v[180:181], v[0:1], 0, s[88:89]
	v_mov_b64_e32 v[0:1], s[2:3]
	s_bfe_u32 s1, s1, 0x20003
	v_mad_u64_u32 v[0:1], s[2:3], v22, s8, v[0:1]
	v_lshlrev_b32_e32 v2, 3, v36
	s_mul_i32 s88, s1, 0x180
	v_mad_i32_i24 v1, v23, s8, v1
	v_and_b32_e32 v24, 56, v2
	s_lshl_b32 s3, s5, 9
	s_lshl_b32 s2, s1, 7
	v_lshl_add_u64 v[0:1], v[0:1], 0, s[88:89]
	v_lshlrev_b32_e32 v8, 1, v24
	v_mov_b32_e32 v9, v189
	s_or_b32 s6, s2, s3
	s_mov_b32 s7, s89
	v_lshl_add_u64 v[26:27], v[0:1], 0, v[8:9]
	v_lshl_add_u64 v[0:1], v[20:21], 0, s[6:7]
	v_readlane_b32 s6, v246, 27
	v_lshlrev_b64 v[28:29], 12, v[0:1]
	v_readlane_b32 s7, v246, 28
	global_load_dwordx4 v[0:3], v[26:27], off
	global_load_dwordx4 v[4:7], v[26:27], off offset:128
	v_lshl_add_u64 v[10:11], s[6:7], 0, v[28:29]
	v_lshl_add_u64 v[30:31], v[10:11], 0, v[8:9]
	global_load_dwordx4 v[8:11], v[26:27], off offset:256
	global_load_dwordx4 v[12:15], v[30:31], off
	s_mov_b32 s1, 0x40000
	v_add_co_u32_e32 v32, vcc, s1, v30
	v_and_b32_e32 v37, 31, v36
	s_nop 0
	v_addc_co_u32_e32 v33, vcc, 0, v31, vcc
	global_load_dwordx4 v[16:19], v[32:33], off
	s_movk_i32 s1, 0xc8
	v_mov_b64_e32 v[34:35], s[84:85]
	v_lshlrev_b32_e32 v21, 7, v20
	v_mad_u64_u32 v[182:183], s[6:7], v20, s1, v[24:25]
	v_or_b32_e32 v180, v180, v37
	v_sub_u32_e32 v196, v182, v21
	v_mad_u64_u32 v[20:21], s[6:7], v180, s8, v[34:35]
	v_bfe_u32 v191, v36, 5, 1
	v_mad_i32_i24 v21, v181, s8, v21
	v_lshlrev_b32_e32 v188, 4, v191
	v_lshl_add_u64 v[20:21], v[20:21], 0, s[88:89]
	v_lshl_add_u64 v[20:21], v[20:21], 0, v[188:189]
	global_load_dwordx4 v[140:143], v[20:21], off
	global_load_dwordx4 v[136:139], v[20:21], off offset:32
	global_load_dwordx4 v[132:135], v[20:21], off offset:64
	global_load_dwordx4 v[128:131], v[20:21], off offset:96
	global_load_dwordx4 v[124:127], v[20:21], off offset:128
	global_load_dwordx4 v[120:123], v[20:21], off offset:160
	global_load_dwordx4 v[116:119], v[20:21], off offset:192
	global_load_dwordx4 v[112:115], v[20:21], off offset:224
	global_load_dwordx4 v[108:111], v[20:21], off offset:256
	global_load_dwordx4 v[104:107], v[20:21], off offset:288
	global_load_dwordx4 v[100:103], v[20:21], off offset:320
	global_load_dwordx4 v[96:99], v[20:21], off offset:352
	s_mov_b32 s1, 0x18000
	v_add_co_u32_e32 v24, vcc, s1, v26
	v_lshl_add_u32 v38, v182, 1, 0
	s_nop 0
	v_addc_co_u32_e32 v25, vcc, 0, v27, vcc
	v_lshl_add_u32 v39, v196, 1, 0
	s_barrier
	v_readlane_b32 s6, v244, 25
	v_readlane_b32 s7, v244, 26
	v_mul_u32_u24_e32 v197, 0x190, v37
	v_mul_u32_u24_e32 v195, 0x90, v37
	s_mov_b32 s3, 0
	v_mov_b32_e32 v199, 0xf149f2ca
	v_mov_b32_e32 v194, 0
	s_waitcnt vmcnt(16)
	ds_write_b128 v38, v[0:3]
	s_waitcnt vmcnt(15)
	ds_write_b128 v38, v[4:7] offset:128
	s_waitcnt vmcnt(14)
	ds_write_b128 v38, v[8:11] offset:256
	s_waitcnt vmcnt(13)
	ds_write_b128 v39, v[12:15] offset:25600
	s_waitcnt vmcnt(12)
	ds_write_b128 v39, v[16:19] offset:34816
	s_waitcnt lgkmcnt(0)
	s_barrier
	global_load_dwordx4 v[144:147], v[24:25], off
	global_load_dwordx4 v[148:151], v[24:25], off offset:128
	global_load_dwordx4 v[152:155], v[24:25], off offset:256
	global_load_dwordx4 v[156:159], v[30:31], off offset:128
	global_load_dwordx4 v[160:163], v[32:33], off offset:128
	v_mbcnt_hi_u32_b32 v0, -1, v224
	v_and_b32_e32 v2, 64, v0
	v_xor_b32_e32 v1, 32, v0
	v_add_u32_e32 v2, 64, v2
	v_cmp_lt_i32_e32 vcc, v1, v2
	v_mov_b32_e32 v14, v189
	v_mov_b32_e32 v15, v189
	v_cndmask_b32_e32 v0, v0, v1, vcc
	v_lshlrev_b32_e32 v183, 2, v0
	v_lshlrev_b32_e32 v0, 4, v36
	v_and_b32_e32 v2, 0x70, v0
	v_or_b32_e32 v28, v28, v2
	v_mov_b64_e32 v[0:1], s[88:89]
	v_lshl_add_u64 v[184:185], s[6:7], 0, v[28:29]
	v_mad_u64_u32 v[0:1], s[6:7], v22, s8, v[0:1]
	v_readlane_b32 s6, v244, 27
	v_mad_i32_i24 v1, v23, s8, v1
	v_or_b32_e32 v0, v0, v2
	v_readlane_b32 s7, v244, 28
	v_mov_b32_e32 v2, v189
	v_mov_b32_e32 v3, v189
	v_lshl_add_u64 v[186:187], s[6:7], 0, v[0:1]
	v_mov_b32_e32 v0, v189
	v_mov_b32_e32 v1, v189
	v_mov_b32_e32 v4, v189
	v_mov_b32_e32 v5, v189
	v_mov_b32_e32 v6, v189
	v_mov_b32_e32 v7, v189
	v_mov_b32_e32 v8, v189
	v_mov_b32_e32 v9, v189
	v_mov_b32_e32 v10, v189
	v_mov_b32_e32 v11, v189
	v_mov_b32_e32 v12, v189
	v_mov_b32_e32 v13, v189
	v_mov_b64_e32 v[30:31], v[14:15]
	v_mov_b64_e32 v[46:47], v[14:15]
	v_mov_b64_e32 v[62:63], v[14:15]
	v_mov_b64_e32 v[28:29], v[12:13]
	v_mov_b64_e32 v[26:27], v[10:11]
	v_mov_b64_e32 v[24:25], v[8:9]
	v_mov_b64_e32 v[22:23], v[6:7]
	v_mov_b64_e32 v[20:21], v[4:5]
	v_mov_b64_e32 v[18:19], v[2:3]
	v_mov_b64_e32 v[16:17], v[0:1]
	v_mov_b64_e32 v[44:45], v[12:13]
	v_mov_b64_e32 v[42:43], v[10:11]
	v_mov_b64_e32 v[40:41], v[8:9]
	v_mov_b64_e32 v[38:39], v[6:7]
	v_mov_b64_e32 v[36:37], v[4:5]
	v_mov_b64_e32 v[34:35], v[2:3]
	v_mov_b64_e32 v[32:33], v[0:1]
	v_mov_b64_e32 v[60:61], v[12:13]
	v_mov_b64_e32 v[58:59], v[10:11]
	v_mov_b64_e32 v[56:57], v[8:9]
	v_mov_b64_e32 v[54:55], v[6:7]
	v_mov_b64_e32 v[52:53], v[4:5]
	v_mov_b64_e32 v[50:51], v[2:3]
	v_mov_b64_e32 v[48:49], v[0:1]

; #define MFMA(a, b, c) __builtin_amdgcn_mfma_f32_32x32x16_bf16((a), (b), (c), 0, 0, 0)
; DI void attn_item(const Params& p, int seq, int hd, int qblk, char* smem, int tid_) {
;     ...
;     float ps = 0.f;
; #pragma unroll
;     for (int kb2 = 0; kb2 < 2; kb2++)
; #pragma unroll
;       for (int i = 0; i < 16; i++) {
;         float pv = __builtin_amdgcn_exp2f(st[kb2][i] - m);
;         st[kb2][i] = pv;
;         ps += pv;
;       }
;     lsum += ps;
;     __builtin_amdgcn_sched_barrier(0);
; #pragma unroll
;     for (int g = 0; g < 16; g++) {
;       const int kb2 = g >> 3, c = (g >> 2) & 1;
;       unsigned pk[4];
; #pragma unroll
;       for (int j = 0; j < 4; j++) pk[j] = pack2(st[kb2][8 * c + 2 * j], st[kb2][8 * c + 2 * j + 1]);
;       u32x4 pu = {pk[0], pk[1], pk[2], pk[3]};
;       bf16x8 pf = __builtin_bit_cast(bf16x8, pu);
;       o[g & 3] = MFMA(vfr[g & 3], pf, o[g & 3]);
;       if (g + 4 < 16) vfr[g & 3] = VFRAG(g + 4);
;       __builtin_amdgcn_sched_barrier(0);
;     }
;     ...
;     if (kt + 1 < 32) {
;       u16* sKn = (u16*)(smem + ((kt + 1) & 1) * 45056);
;       u16* sVn = sKn + 64 * 200;
; #pragma unroll
;       for (int i = 0; i < 3; i++) *(u32x4*)(sKn + kl + 64 * i) = rk[i];
; #pragma unroll
;       for (int i = 0; i < 2; i++) *(u32x4*)(sVn + vl + 64 * i * 72) = rv[i];
;     }
;     __syncthreads();
;     if (kt + 2 < 32) {
; #pragma unroll
;       for (int i = 0; i < 3; i++) rk[i] = *(const u32x4*)(kg + (size_t)(kt + 2) * 64 * 768 + 64 * i);
; #pragma unroll
;       for (int i = 0; i < 2; i++) rv[i] = *(const u32x4*)(vg + (size_t)(64 * i) * 2048 + (kt + 2) * 64);
;     }
;   }
;   lsum += __shfl_xor(lsum, 32);
;   const float inv = 1.f / lsum;
;   u16* orow = mixed + qrow * 1024 + 256 + hd * 128;
; #pragma unroll
;   for (int db = 0; db < 4; db++)
; #pragma unroll
;     for (int g = 0; g < 4; g++) {
;       uint2 ov;
;       ov.x = pack2(o[db][4 * g] * inv, o[db][4 * g + 1] * inv);
;       ov.y = pack2(o[db][4 * g + 2] * inv, o[db][4 * g + 3] * inv);
;       *(uint2*)(orow + 32 * db + 8 * g + 4 * h) = ov;
;     }
.LBB0_634:
	v_sub_f32_e32 v64, v64, v112
	v_exp_f32_e32 v64, v64
	v_sub_f32_e32 v65, v65, v112
	v_sub_f32_e32 v66, v66, v112
	v_exp_f32_e32 v65, v65
	v_exp_f32_e32 v66, v66
	v_sub_f32_e32 v67, v67, v112
	v_exp_f32_e32 v67, v67
	v_sub_f32_e32 v68, v68, v112
	v_add_f32_e32 v113, 0, v64
	v_exp_f32_e32 v68, v68
	v_sub_f32_e32 v69, v69, v112
	v_add_f32_e32 v113, v65, v113
	v_exp_f32_e32 v69, v69
	v_add_f32_e32 v113, v66, v113
	v_add_f32_e32 v113, v67, v113
	v_add_f32_e32 v113, v68, v113
	v_sub_f32_e32 v72, v72, v112
	v_sub_f32_e32 v73, v73, v112
	v_exp_f32_e32 v114, v72
	v_add_f32_e32 v72, v69, v113
	v_exp_f32_e32 v113, v73
	v_sub_f32_e32 v73, v74, v112
	v_exp_f32_e32 v115, v73
	v_sub_f32_e32 v73, v75, v112
	v_exp_f32_e32 v116, v73
	v_sub_f32_e32 v73, v76, v112
	v_exp_f32_e32 v117, v73
	v_sub_f32_e32 v73, v77, v112
	v_exp_f32_e32 v118, v73
	v_sub_f32_e32 v73, v78, v112
	v_exp_f32_e32 v119, v73
	v_sub_f32_e32 v73, v79, v112
	v_exp_f32_e32 v120, v73
	v_sub_f32_e32 v73, v80, v112
	v_exp_f32_e32 v121, v73
	v_sub_f32_e32 v73, v81, v112
	v_sub_f32_e32 v70, v70, v112
	v_exp_f32_e32 v122, v73
	v_sub_f32_e32 v73, v82, v112
	v_exp_f32_e32 v70, v70
	v_sub_f32_e32 v71, v71, v112
	v_exp_f32_e32 v123, v73
	v_sub_f32_e32 v73, v83, v112
	v_exp_f32_e32 v71, v71
	v_exp_f32_e32 v124, v73
	v_sub_f32_e32 v73, v84, v112
	v_exp_f32_e32 v84, v73
	v_sub_f32_e32 v73, v85, v112
	v_exp_f32_e32 v85, v73
	v_sub_f32_e32 v73, v86, v112
	v_add_f32_e32 v72, v70, v72
	v_exp_f32_e32 v86, v73
	v_sub_f32_e32 v73, v87, v112
	v_add_f32_e32 v72, v71, v72
	v_exp_f32_e32 v87, v73
	v_sub_f32_e32 v73, v88, v112
	v_add_f32_e32 v72, v114, v72
	v_exp_f32_e32 v88, v73
	v_sub_f32_e32 v73, v89, v112
	v_add_f32_e32 v72, v113, v72
	v_exp_f32_e32 v89, v73
	v_sub_f32_e32 v73, v90, v112
	v_add_f32_e32 v72, v115, v72
	v_exp_f32_e32 v90, v73
	v_sub_f32_e32 v73, v91, v112
	v_add_f32_e32 v72, v116, v72
	v_exp_f32_e32 v91, v73
	v_sub_f32_e32 v73, v92, v112
	v_add_f32_e32 v72, v117, v72
	v_exp_f32_e32 v92, v73
	v_sub_f32_e32 v73, v93, v112
	v_exp_f32_e32 v93, v73
	v_sub_f32_e32 v73, v94, v112
	v_add_f32_e32 v72, v118, v72
	s_movk_i32 s5, 0x600
	v_exp_f32_e32 v94, v73
	v_sub_f32_e32 v73, v95, v112
	v_add_f32_e32 v72, v119, v72
	v_exp_f32_e32 v95, v73
	v_add_f32_e32 v112, v120, v72
	v_cvt_pk_bf16_f32 v64, v64, v65
	v_cvt_pk_bf16_f32 v65, v66, v67
	v_cvt_pk_bf16_f32 v66, v68, v69
	v_cvt_pk_bf16_f32 v67, v70, v71
	v_readlane_b32 s1, v244, 32
	s_waitcnt lgkmcnt(3)
	v_mfma_f32_32x32x16_bf16 v[48:63], v[108:111], v[64:67], v[48:63]
	v_add3_u32 v108, s1, v195, v188
	ds_read_b128 v[68:71], v108 offset:32
	ds_read_b128 v[72:75], v108 offset:4640
	s_waitcnt lgkmcnt(4)
	v_mfma_f32_32x32x16_bf16 v[32:47], v[104:107], v[64:67], v[32:47]
	ds_read_b128 v[76:79], v108 offset:9248
	s_waitcnt lgkmcnt(4)
	v_mfma_f32_32x32x16_bf16 v[16:31], v[100:103], v[64:67], v[16:31]
	s_waitcnt lgkmcnt(3)
	v_mfma_f32_32x32x16_bf16 v[0:15], v[96:99], v[64:67], v[0:15]
	ds_read_b128 v[64:67], v108 offset:13856
	v_cvt_pk_bf16_f32 v80, v114, v113
	v_cvt_pk_bf16_f32 v81, v115, v116
	v_cvt_pk_bf16_f32 v82, v117, v118
	v_cvt_pk_bf16_f32 v83, v119, v120
	s_waitcnt lgkmcnt(3)
	s_nop 0
	v_mfma_f32_32x32x16_bf16 v[48:63], v[68:71], v[80:83], v[48:63]
	ds_read_b128 v[68:71], v108 offset:64
	s_waitcnt lgkmcnt(3)
	v_mfma_f32_32x32x16_bf16 v[32:47], v[72:75], v[80:83], v[32:47]
	ds_read_b128 v[72:75], v108 offset:4672
	s_waitcnt lgkmcnt(3)
	v_mfma_f32_32x32x16_bf16 v[16:31], v[76:79], v[80:83], v[16:31]
	ds_read_b128 v[76:79], v108 offset:9280
	s_waitcnt lgkmcnt(3)
	v_mfma_f32_32x32x16_bf16 v[0:15], v[64:67], v[80:83], v[0:15]
	ds_read_b128 v[64:67], v108 offset:13888
	v_cvt_pk_bf16_f32 v80, v121, v122
	v_cvt_pk_bf16_f32 v81, v123, v124
	v_cvt_pk_bf16_f32 v82, v84, v85
	v_cvt_pk_bf16_f32 v83, v86, v87
	s_waitcnt lgkmcnt(3)
	s_nop 0
	v_mfma_f32_32x32x16_bf16 v[48:63], v[68:71], v[80:83], v[48:63]
	ds_read_b128 v[68:71], v108 offset:96
	s_waitcnt lgkmcnt(3)
	v_mfma_f32_32x32x16_bf16 v[32:47], v[72:75], v[80:83], v[32:47]
	ds_read_b128 v[72:75], v108 offset:4704
	s_waitcnt lgkmcnt(3)
	v_mfma_f32_32x32x16_bf16 v[16:31], v[76:79], v[80:83], v[16:31]
	ds_read_b128 v[76:79], v108 offset:9312
	s_waitcnt lgkmcnt(3)
	v_mfma_f32_32x32x16_bf16 v[0:15], v[64:67], v[80:83], v[0:15]
	ds_read_b128 v[64:67], v108 offset:13920
	v_cvt_pk_bf16_f32 v80, v88, v89
	v_cvt_pk_bf16_f32 v81, v90, v91
	v_cvt_pk_bf16_f32 v82, v92, v93
	v_cvt_pk_bf16_f32 v83, v94, v95
	s_waitcnt lgkmcnt(3)
	s_nop 0
	v_mfma_f32_32x32x16_bf16 v[48:63], v[68:71], v[80:83], v[48:63]
	s_waitcnt lgkmcnt(2)
	v_mfma_f32_32x32x16_bf16 v[32:47], v[72:75], v[80:83], v[32:47]
	s_waitcnt lgkmcnt(1)
	v_mfma_f32_32x32x16_bf16 v[16:31], v[76:79], v[80:83], v[16:31]
	s_waitcnt lgkmcnt(0)
	v_mfma_f32_32x32x16_bf16 v[0:15], v[64:67], v[80:83], v[0:15]
	v_add_f32_e32 v64, v121, v112
	v_add_f32_e32 v64, v122, v64
	v_add_f32_e32 v64, v123, v64
	v_add_f32_e32 v64, v124, v64
	v_add_f32_e32 v64, v84, v64
	v_add_f32_e32 v64, v85, v64
	v_add_f32_e32 v64, v86, v64
	v_add_f32_e32 v64, v87, v64
	v_add_f32_e32 v64, v88, v64
	v_add_f32_e32 v64, v89, v64
	v_add_f32_e32 v64, v90, v64
	v_add_f32_e32 v64, v91, v64
	v_add_f32_e32 v64, v92, v64
	v_add_f32_e32 v64, v93, v64
	v_add_f32_e32 v64, v94, v64
	v_add_f32_e32 v64, v95, v64
	v_add_f32_e32 v64, v194, v64
	ds_bpermute_b32 v65, v183, v64
	s_lshl_b32 s88, s2, 1
	v_lshlrev_b32_e32 v188, 3, v191
	s_mov_b32 s1, 0x2f20000
	s_mov_b64 s[2:3], 0x2f20300
	s_waitcnt lgkmcnt(0)
	v_add_f32_e32 v64, v64, v65
	v_div_scale_f32 v65, s[6:7], v64, v64, 1.0
	v_rcp_f32_e32 v66, v65
	v_div_scale_f32 v67, vcc, 1.0, v64, 1.0
	v_fma_f32 v68, -v65, v66, 1.0
	v_fmac_f32_e32 v66, v68, v66
	v_mul_f32_e32 v68, v67, v66
	v_fma_f32 v69, -v65, v68, v67
	v_fmac_f32_e32 v68, v69, v66
	v_fma_f32 v65, -v65, v68, v67
	v_div_fmas_f32 v65, v65, v66, v68
	v_lshlrev_b64 v[66:67], 11, v[180:181]
	v_lshl_add_u64 v[66:67], s[80:81], 0, v[66:67]
	v_div_fixup_f32 v64, v65, v64, 1.0
	v_lshl_add_u64 v[66:67], v[66:67], 0, s[88:89]
	v_lshl_add_u64 v[66:67], v[66:67], 0, v[188:189]
	v_pk_mul_f32 v[48:49], v[48:49], v[64:65] op_sel_hi:[1,0]
	v_pk_mul_f32 v[50:51], v[50:51], v[64:65] op_sel_hi:[1,0]
	v_cvt_pk_bf16_f32 v48, v48, v49
	v_cvt_pk_bf16_f32 v49, v50, v51
	v_add_co_u32_e32 v50, vcc, s1, v66
	v_pk_mul_f32 v[32:33], v[32:33], v[64:65] op_sel_hi:[1,0]
	v_pk_mul_f32 v[34:35], v[34:35], v[64:65] op_sel_hi:[1,0]
	v_pk_mul_f32 v[16:17], v[16:17], v[64:65] op_sel_hi:[1,0]
	v_pk_mul_f32 v[18:19], v[18:19], v[64:65] op_sel_hi:[1,0]
	v_pk_mul_f32 v[0:1], v[0:1], v[64:65] op_sel_hi:[1,0]
	v_pk_mul_f32 v[2:3], v[2:3], v[64:65] op_sel_hi:[1,0]
	v_lshl_add_u64 v[68:69], v[66:67], 0, s[2:3]
	v_addc_co_u32_e32 v51, vcc, 0, v67, vcc
	v_cvt_pk_bf16_f32 v32, v32, v33
	v_cvt_pk_bf16_f32 v33, v34, v35
	v_cvt_pk_bf16_f32 v16, v16, v17
	v_cvt_pk_bf16_f32 v17, v18, v19
	v_cvt_pk_bf16_f32 v0, v0, v1
	v_cvt_pk_bf16_f32 v1, v2, v3
	s_barrier
; DI void attn_item(const Params& p, int seq, int hd, int qblk, char* smem, int tid_) {
;     ...
; #pragma unroll
;   for (int db = 0; db < 4; db++)
; #pragma unroll
;     for (int g = 0; g < 4; g++) {
;       uint2 ov;
;       ov.x = pack2(o[db][4 * g] * inv, o[db][4 * g + 1] * inv);
;       ov.y = pack2(o[db][4 * g + 2] * inv, o[db][4 * g + 3] * inv);
;       *(uint2*)(orow + 32 * db + 8 * g + 4 * h) = ov;
;     }
	global_store_dwordx2 v[50:51], v[48:49], off offset:768
	v_pk_mul_f32 v[48:49], v[52:53], v[64:65] op_sel_hi:[1,0]
	v_pk_mul_f32 v[50:51], v[54:55], v[64:65] op_sel_hi:[1,0]
	global_store_dwordx2 v[68:69], v[32:33], off offset:64
	v_pk_mul_f32 v[32:33], v[36:37], v[64:65] op_sel_hi:[1,0]
	v_pk_mul_f32 v[34:35], v[38:39], v[64:65] op_sel_hi:[1,0]
	global_store_dwordx2 v[68:69], v[16:17], off offset:128
	v_pk_mul_f32 v[16:17], v[20:21], v[64:65] op_sel_hi:[1,0]
	v_pk_mul_f32 v[18:19], v[22:23], v[64:65] op_sel_hi:[1,0]
	global_store_dwordx2 v[68:69], v[0:1], off offset:192
	v_pk_mul_f32 v[0:1], v[4:5], v[64:65] op_sel_hi:[1,0]
	v_pk_mul_f32 v[2:3], v[6:7], v[64:65] op_sel_hi:[1,0]
	v_cvt_pk_bf16_f32 v48, v48, v49
	v_cvt_pk_bf16_f32 v49, v50, v51
	v_cvt_pk_bf16_f32 v32, v32, v33
	v_cvt_pk_bf16_f32 v33, v34, v35
	v_cvt_pk_bf16_f32 v16, v16, v17
	v_cvt_pk_bf16_f32 v17, v18, v19
	v_cvt_pk_bf16_f32 v0, v0, v1
	v_cvt_pk_bf16_f32 v1, v2, v3
	global_store_dwordx2 v[68:69], v[48:49], off offset:16
	v_pk_mul_f32 v[48:49], v[56:57], v[64:65] op_sel_hi:[1,0]
	v_pk_mul_f32 v[50:51], v[58:59], v[64:65] op_sel_hi:[1,0]
	global_store_dwordx2 v[68:69], v[32:33], off offset:80
	v_pk_mul_f32 v[32:33], v[40:41], v[64:65] op_sel_hi:[1,0]
	v_pk_mul_f32 v[34:35], v[42:43], v[64:65] op_sel_hi:[1,0]
	global_store_dwordx2 v[68:69], v[16:17], off offset:144
	v_pk_mul_f32 v[16:17], v[24:25], v[64:65] op_sel_hi:[1,0]
	v_pk_mul_f32 v[18:19], v[26:27], v[64:65] op_sel_hi:[1,0]
	global_store_dwordx2 v[68:69], v[0:1], off offset:208
	v_pk_mul_f32 v[0:1], v[8:9], v[64:65] op_sel_hi:[1,0]
	v_pk_mul_f32 v[2:3], v[10:11], v[64:65] op_sel_hi:[1,0]
	v_cvt_pk_bf16_f32 v48, v48, v49
	v_cvt_pk_bf16_f32 v49, v50, v51
	v_cvt_pk_bf16_f32 v32, v32, v33
	v_cvt_pk_bf16_f32 v33, v34, v35
	v_cvt_pk_bf16_f32 v16, v16, v17
	v_cvt_pk_bf16_f32 v17, v18, v19
	v_cvt_pk_bf16_f32 v0, v0, v1
	v_cvt_pk_bf16_f32 v1, v2, v3
	global_store_dwordx2 v[68:69], v[48:49], off offset:32
	v_pk_mul_f32 v[48:49], v[60:61], v[64:65] op_sel_hi:[1,0]
	v_pk_mul_f32 v[50:51], v[62:63], v[64:65] op_sel_hi:[1,0]
	global_store_dwordx2 v[68:69], v[32:33], off offset:96
	v_pk_mul_f32 v[32:33], v[44:45], v[64:65] op_sel_hi:[1,0]
	v_pk_mul_f32 v[34:35], v[46:47], v[64:65] op_sel_hi:[1,0]
	global_store_dwordx2 v[68:69], v[16:17], off offset:160
	v_pk_mul_f32 v[16:17], v[28:29], v[64:65] op_sel_hi:[1,0]
	v_pk_mul_f32 v[18:19], v[30:31], v[64:65] op_sel_hi:[1,0]
	global_store_dwordx2 v[68:69], v[0:1], off offset:224
	v_pk_mul_f32 v[0:1], v[12:13], v[64:65] op_sel_hi:[1,0]
	v_pk_mul_f32 v[2:3], v[14:15], v[64:65] op_sel_hi:[1,0]
	v_cvt_pk_bf16_f32 v48, v48, v49
	v_cvt_pk_bf16_f32 v49, v50, v51
	v_cvt_pk_bf16_f32 v32, v32, v33
	v_cvt_pk_bf16_f32 v33, v34, v35
	v_cvt_pk_bf16_f32 v16, v16, v17
	v_cvt_pk_bf16_f32 v17, v18, v19
	v_cvt_pk_bf16_f32 v0, v0, v1
	v_cvt_pk_bf16_f32 v1, v2, v3
	global_store_dwordx2 v[68:69], v[48:49], off offset:48
	global_store_dwordx2 v[68:69], v[32:33], off offset:112
	global_store_dwordx2 v[68:69], v[16:17], off offset:176
	global_store_dwordx2 v[68:69], v[0:1], off offset:240
	s_setprio 0
	s_mov_b64 s[2:3], 0
	s_movk_i32 s66, 0x1b80
	s_movk_i32 s67, 0xffb4
